# v15
# baseline (speedup 1.0000x reference)
; #define LAS __attribute__((address_space(3)))
; DI unsigned pk2(float lo, float hi) { f32x2 v = {lo, hi}; bf16x2_t b = __builtin_convertvector(v, bf16x2_t); return __builtin_bit_cast(unsigned, b); }
; DI float bflo(unsigned u) { return __uint_as_float(u << 16); }
; DI float bfhi(unsigned u) { return __uint_as_float(u & 0xffff0000u); }
; DI void stage_ld(u32x4 (&regs)[4], const bf16_t* src, size_t rstride, int tid) {
;     ...
;     for (int i = 0; i < 4; ++i) { const int id = tid + 512 * i, r = id & 127, c8 = (id >> 7) * 8; regs[i] = *(const u32x4*)(src + (size_t)r * rstride + c8); }
; }
; template <bool SCALE> DI void stage_st(LAS unsigned char* dst, const u32x4 (&regs)[4], const LAS float* rs, const float* cs, int tid) {
; #pragma unroll
;     for (int i = 0; i < 4; ++i) {
;         const int id = tid + 512 * i, r = id & 127, c8 = (id >> 7) * 8;
;         const u32x4 v = regs[i];
;         float f0 = bflo(v.x), f1 = bfhi(v.x), f2 = bflo(v.y), f3 = bfhi(v.y), f4 = bflo(v.z), f5 = bfhi(v.z), f6 = bflo(v.w), f7 = bfhi(v.w);
;         if (SCALE) { const float s = rs[r]; const f32x4 c0 = *(const f32x4*)(cs + c8), c1 = *(const f32x4*)(cs + c8 + 4);
;             f0 *= s * c0[0]; f1 *= s * c0[1]; f2 *= s * c0[2]; f3 *= s * c0[3]; f4 *= s * c1[0]; f5 *= s * c1[1]; f6 *= s * c1[2]; f7 *= s * c1[3]; }
;         LAS unsigned char* d = dst + (c8 * TP + r) * 2;
;         if (SCALE) {
;             *(LAS unsigned short*)(d + 0 * TP * 2) = (unsigned short)pk2(f0, 0.f); *(LAS unsigned short*)(d + 1 * TP * 2) = (unsigned short)pk2(f1, 0.f);
;             *(LAS unsigned short*)(d + 2 * TP * 2) = (unsigned short)pk2(f2, 0.f); *(LAS unsigned short*)(d + 3 * TP * 2) = (unsigned short)pk2(f3, 0.f);
;             *(LAS unsigned short*)(d + 4 * TP * 2) = (unsigned short)pk2(f4, 0.f); *(LAS unsigned short*)(d + 5 * TP * 2) = (unsigned short)pk2(f5, 0.f);
;             *(LAS unsigned short*)(d + 6 * TP * 2) = (unsigned short)pk2(f6, 0.f); *(LAS unsigned short*)(d + 7 * TP * 2) = (unsigned short)pk2(f7, 0.f);
.LBB0_434:
	v_lshl_add_u64 v[0:1], v[98:99], 0, s[18:19]
	global_load_dwordx4 v[10:13], v[0:1], off
	v_lshl_add_u64 v[0:1], v[96:97], 0, s[18:19]
	global_load_dwordx4 v[14:17], v[0:1], off
	v_lshl_add_u64 v[0:1], v[94:95], 0, s[18:19]
	global_load_dwordx4 v[4:7], v[0:1], off
	v_lshl_add_u64 v[0:1], v[92:93], 0, s[18:19]
	v_lshl_add_u64 v[18:19], s[8:9], 0, v[66:67]
	global_load_dwordx4 v[0:3], v[0:1], off
	ds_read_b32 v8, v109
	s_waitcnt vmcnt(3)
	v_lshlrev_b32_e32 v9, 16, v10
	v_and_b32_e32 v22, 0xffff0000, v10
	v_lshlrev_b32_e32 v23, 16, v11
	v_and_b32_e32 v24, 0xffff0000, v11
	v_lshlrev_b32_e32 v25, 16, v12
	v_and_b32_e32 v26, 0xffff0000, v12
	v_lshlrev_b32_e32 v27, 16, v13
	v_and_b32_e32 v28, 0xffff0000, v13
	global_load_dwordx4 v[10:13], v[18:19], off offset:16
	s_nop 0
	global_load_dwordx4 v[18:21], v[18:19], off
	s_waitcnt vmcnt(1) lgkmcnt(0)
	v_mul_f32_e32 v10, v8, v10
	s_waitcnt vmcnt(0)
	v_mul_f32_e32 v18, v8, v18
	v_mul_f32_e32 v9, v18, v9
	v_mul_f32_e32 v18, v8, v19
	v_mul_f32_e32 v18, v18, v22
	v_mul_f32_e32 v19, v8, v20
	v_cvt_pk_bf16_f32 v9, v9, s0
	v_mul_f32_e32 v19, v19, v23
	v_mul_f32_e32 v20, v8, v21
	ds_write_b16 v120, v9
	v_cvt_pk_bf16_f32 v9, v18, s0
	v_mul_f32_e32 v20, v20, v24
	ds_write_b16 v120, v9 offset:272
	v_cvt_pk_bf16_f32 v9, v19, s0
	v_mul_f32_e32 v10, v10, v25
	v_mul_f32_e32 v11, v8, v11
	ds_write_b16 v120, v9 offset:544
	v_cvt_pk_bf16_f32 v9, v20, s0
	v_mul_f32_e32 v11, v11, v26
	v_mul_f32_e32 v12, v8, v12
	ds_write_b16 v120, v9 offset:816
	v_cvt_pk_bf16_f32 v9, v10, s0
	v_mul_f32_e32 v12, v12, v27
	v_mul_f32_e32 v13, v8, v13
	ds_write_b16 v120, v9 offset:1088
	v_cvt_pk_bf16_f32 v9, v11, s0
	v_mul_f32_e32 v13, v13, v28
	ds_write_b16 v120, v9 offset:1360
	v_cvt_pk_bf16_f32 v9, v12, s0
	ds_write_b16 v120, v9 offset:1632
	v_cvt_pk_bf16_f32 v9, v13, s0
	ds_write_b16 v120, v9 offset:1904
	v_lshlrev_b32_e32 v9, 16, v14
	v_and_b32_e32 v18, 0xffff0000, v14
	v_lshlrev_b32_e32 v19, 16, v15
	v_and_b32_e32 v20, 0xffff0000, v15
	v_lshl_add_u64 v[14:15], s[8:9], 0, v[64:65]
	v_lshlrev_b32_e32 v21, 16, v16
	v_and_b32_e32 v22, 0xffff0000, v16
	v_lshlrev_b32_e32 v23, 16, v17
	v_and_b32_e32 v24, 0xffff0000, v17
	global_load_dwordx4 v[10:13], v[14:15], off offset:16
	s_nop 0
	global_load_dwordx4 v[14:17], v[14:15], off
	s_waitcnt vmcnt(1)
	v_mul_f32_e32 v10, v8, v10
	s_waitcnt vmcnt(0)
	v_mul_f32_e32 v14, v8, v14
	v_mul_f32_e32 v9, v14, v9
	v_mul_f32_e32 v14, v8, v15
	v_mul_f32_e32 v14, v14, v18
	v_mul_f32_e32 v15, v8, v16
	v_cvt_pk_bf16_f32 v9, v9, s0
	v_mul_f32_e32 v15, v15, v19
	v_mul_f32_e32 v16, v8, v17
	ds_write_b16 v121, v9
	v_cvt_pk_bf16_f32 v9, v14, s0
	v_mul_f32_e32 v16, v16, v20
	ds_write_b16 v121, v9 offset:272
	v_cvt_pk_bf16_f32 v9, v15, s0
	v_mul_f32_e32 v10, v10, v21
	v_mul_f32_e32 v11, v8, v11
	ds_write_b16 v121, v9 offset:544
	v_cvt_pk_bf16_f32 v9, v16, s0
	v_mul_f32_e32 v11, v11, v22
	v_mul_f32_e32 v12, v8, v12
	ds_write_b16 v121, v9 offset:816
	v_cvt_pk_bf16_f32 v9, v10, s0
	v_mul_f32_e32 v12, v12, v23
	v_mul_f32_e32 v13, v8, v13
	ds_write_b16 v121, v9 offset:1088
	v_cvt_pk_bf16_f32 v9, v11, s0
	v_mul_f32_e32 v13, v13, v24
	ds_write_b16 v121, v9 offset:1360
	v_cvt_pk_bf16_f32 v9, v12, s0
	ds_write_b16 v121, v9 offset:1632
	v_cvt_pk_bf16_f32 v9, v13, s0
	ds_write_b16 v121, v9 offset:1904
	v_lshl_add_u64 v[10:11], s[8:9], 0, v[62:63]
	v_lshlrev_b32_e32 v9, 16, v4
	v_and_b32_e32 v14, 0xffff0000, v4
	v_lshlrev_b32_e32 v15, 16, v5
	v_and_b32_e32 v16, 0xffff0000, v5
	v_lshlrev_b32_e32 v17, 16, v6
	v_and_b32_e32 v18, 0xffff0000, v6
	v_lshlrev_b32_e32 v19, 16, v7
	v_and_b32_e32 v20, 0xffff0000, v7
	global_load_dwordx4 v[4:7], v[10:11], off offset:16
	s_nop 0
	global_load_dwordx4 v[10:13], v[10:11], off
	s_waitcnt vmcnt(1)
	v_mul_f32_e32 v4, v8, v4
	s_waitcnt vmcnt(0)
	v_mul_f32_e32 v10, v8, v10
	v_mul_f32_e32 v9, v10, v9
	v_mul_f32_e32 v10, v8, v11
	v_mul_f32_e32 v4, v4, v17
	v_mul_f32_e32 v5, v8, v5
	v_mul_f32_e32 v10, v10, v14
	v_mul_f32_e32 v11, v8, v12
	v_mul_f32_e32 v5, v5, v18
	v_mul_f32_e32 v6, v8, v6
	v_cvt_pk_bf16_f32 v9, v9, s0
	v_cvt_pk_bf16_f32 v4, v4, s0
	v_mul_f32_e32 v11, v11, v15
	v_mul_f32_e32 v12, v8, v13
	v_mul_f32_e32 v6, v6, v19
	v_mul_f32_e32 v7, v8, v7
	ds_write_b16 v122, v9
	v_cvt_pk_bf16_f32 v9, v10, s0
	ds_write_b16 v122, v4 offset:1088
	v_cvt_pk_bf16_f32 v4, v5, s0
	v_mul_f32_e32 v12, v12, v16
	v_mul_f32_e32 v7, v7, v20
	ds_write_b16 v122, v9 offset:272
	v_cvt_pk_bf16_f32 v9, v11, s0
	ds_write_b16 v122, v4 offset:1360
	v_cvt_pk_bf16_f32 v4, v6, s0
	ds_write_b16 v122, v9 offset:544
	v_cvt_pk_bf16_f32 v9, v12, s0
	ds_write_b16 v122, v4 offset:1632
	v_cvt_pk_bf16_f32 v4, v7, s0
	ds_write_b16 v122, v9 offset:816
	ds_write_b16 v122, v4 offset:1904
	v_lshlrev_b32_e32 v6, 16, v0
	v_and_b32_e32 v7, 0xffff0000, v0
	v_lshlrev_b32_e32 v9, 16, v1
	v_and_b32_e32 v14, 0xffff0000, v1
	v_lshl_add_u64 v[0:1], s[8:9], 0, v[58:59]
	v_lshlrev_b32_e32 v15, 16, v2
	v_and_b32_e32 v16, 0xffff0000, v2
	v_lshlrev_b32_e32 v17, 16, v3
	v_and_b32_e32 v18, 0xffff0000, v3
	global_load_dwordx4 v[2:5], v[0:1], off offset:16
	global_load_dwordx4 v[10:13], v[0:1], off
	s_waitcnt vmcnt(1)
	v_mul_f32_e32 v2, v8, v2
	s_waitcnt vmcnt(0)
; #define LAS __attribute__((address_space(3)))
; DI unsigned pk2(float lo, float hi) { f32x2 v = {lo, hi}; bf16x2_t b = __builtin_convertvector(v, bf16x2_t); return __builtin_bit_cast(unsigned, b); }
; __global__ void __launch_bounds__(NTHR) fwd_kernel(Args args) {
;     ...
;                               for (int i = 0; i < 8; ++i) { const int id = tid + 512 * i, p = id >> 5, q4 = (id & 31) * 4; const f32x4 v = *(const f32x4*)(wsrc + p * 128 + q4);
;                                   *(LAS u32x2*)(lds + 3 * TILE_B + (p * TP + q4) * 2) = (u32x2){pk2(v[0], v[1]), pk2(v[2], v[3])}; } }
;                             __syncthreads();
;                             f32x16 acc[2];
; #pragma unroll
;                             for (int i = 0; i < 2; ++i)
; #pragma unroll
;                                 for (int r = 0; r < 16; ++r) acc[i][r] = 0.f;
;                             tgemm128<false>(acc, lds + 2 * TILE_B, lds + 3 * TILE_B, wid, lane);
;     ...
;                                 const int p = 64 * (wid >> 2) + 32 * nt + r32; const float bias = args.in[I_SGUB][(l * 8 + g) * 128 + p];
;                                 const size_t off = (R0 + p) * RESTW + g * 128 + 32 * (wid & 3) + 4 * hi;
;                                 bf16_t* op = SGUO + (R0 + p) * 1024 + g * 128 + 32 * (wid & 3) + 4 * hi;
; #pragma unroll
;                                 for (int rg = 0; rg < 4; ++rg) {
;                                     const u32x2 su = *(const u32x2*)(REST + off + 8 * rg);
	v_mul_f32_e32 v0, v8, v10
	v_mul_f32_e32 v0, v0, v6
	v_mul_f32_e32 v1, v8, v11
	v_mul_f32_e32 v1, v1, v7
	v_mul_f32_e32 v6, v8, v12
	v_cvt_pk_bf16_f32 v0, v0, s0
	v_mul_f32_e32 v6, v6, v9
	v_mul_f32_e32 v7, v8, v13
	ds_write_b16 v123, v0
	v_cvt_pk_bf16_f32 v0, v1, s0
	v_mul_f32_e32 v7, v7, v14
	ds_write_b16 v123, v0 offset:272
	v_cvt_pk_bf16_f32 v0, v6, s0
	v_mul_f32_e32 v2, v2, v15
	v_mul_f32_e32 v3, v8, v3
	ds_write_b16 v123, v0 offset:544
	v_cvt_pk_bf16_f32 v0, v7, s0
	v_mul_f32_e32 v3, v3, v16
	v_mul_f32_e32 v4, v8, v4
	ds_write_b16 v123, v0 offset:816
	v_cvt_pk_bf16_f32 v0, v2, s0
	v_mul_f32_e32 v4, v4, v17
	v_mul_f32_e32 v5, v8, v5
	ds_write_b16 v123, v0 offset:1088
	v_cvt_pk_bf16_f32 v0, v3, s0
	v_mul_f32_e32 v5, v5, v18
	ds_write_b16 v123, v0 offset:1360
	v_cvt_pk_bf16_f32 v0, v4, s0
	ds_write_b16 v123, v0 offset:1632
	v_cvt_pk_bf16_f32 v0, v5, s0
	ds_write_b16 v123, v0 offset:1904
	v_lshl_add_u64 v[138:139], v[88:89], 0, s[68:69]
	global_load_dwordx4 v[138:141], v[138:139], off
	v_lshl_add_u64 v[142:143], v[86:87], 0, s[68:69]
	global_load_dwordx4 v[142:145], v[142:143], off
	v_lshl_add_u64 v[146:147], v[84:85], 0, s[68:69]
	global_load_dwordx4 v[146:149], v[146:147], off
	v_lshl_add_u64 v[150:151], v[82:83], 0, s[68:69]
	global_load_dwordx4 v[150:153], v[150:151], off
	v_lshl_add_u64 v[154:155], v[80:81], 0, s[68:69]
	global_load_dwordx4 v[154:157], v[154:155], off
	v_lshl_add_u64 v[158:159], v[78:79], 0, s[68:69]
	global_load_dwordx4 v[158:161], v[158:159], off
	v_lshl_add_u64 v[162:163], v[76:77], 0, s[68:69]
	global_load_dwordx4 v[162:165], v[162:163], off
	v_lshl_add_u64 v[166:167], v[74:75], 0, s[68:69]
	global_load_dwordx4 v[166:169], v[166:167], off
	s_waitcnt vmcnt(7)
	v_cvt_pk_bf16_f32 v138, v138, v139
	v_cvt_pk_bf16_f32 v139, v140, v141
	ds_write_b64 v111, v[138:139]
	s_waitcnt vmcnt(6)
	v_cvt_pk_bf16_f32 v142, v142, v143
	v_cvt_pk_bf16_f32 v143, v144, v145
	ds_write_b64 v112, v[142:143]
	s_waitcnt vmcnt(5)
	v_cvt_pk_bf16_f32 v146, v146, v147
	v_cvt_pk_bf16_f32 v147, v148, v149
	ds_write_b64 v113, v[146:147]
	s_waitcnt vmcnt(4)
	v_cvt_pk_bf16_f32 v150, v150, v151
	v_cvt_pk_bf16_f32 v151, v152, v153
	ds_write_b64 v114, v[150:151]
	s_waitcnt vmcnt(3)
	v_cvt_pk_bf16_f32 v154, v154, v155
	v_cvt_pk_bf16_f32 v155, v156, v157
	ds_write_b64 v115, v[154:155]
	s_waitcnt vmcnt(2)
	v_cvt_pk_bf16_f32 v158, v158, v159
	v_cvt_pk_bf16_f32 v159, v160, v161
	ds_write_b64 v116, v[158:159]
	s_waitcnt vmcnt(1)
	v_cvt_pk_bf16_f32 v162, v162, v163
	v_cvt_pk_bf16_f32 v163, v164, v165
	ds_write_b64 v117, v[162:163]
	s_waitcnt vmcnt(0)
	v_cvt_pk_bf16_f32 v166, v166, v167
	v_cvt_pk_bf16_f32 v167, v168, v169
	ds_write_b64 v118, v[166:167]
	s_waitcnt lgkmcnt(0)
	s_barrier
	v_ashrrev_i32_e32 v91, 31, v90
	v_lshl_add_u64 v[170:171], v[90:91], 2, s[12:13]
	v_lshl_add_u64 v[172:173], v[102:103], 0, s[18:19]
	v_lshl_add_u64 v[174:175], v[100:101], 0, s[18:19]
	global_load_dword v176, v[170:171], off
	global_load_dword v196, v[170:171], off offset:128
	global_load_dwordx2 v[178:179], v[172:173], off offset:-32
	global_load_dwordx2 v[180:181], v[172:173], off offset:-16
	global_load_dwordx2 v[182:183], v[172:173], off
	global_load_dwordx2 v[186:187], v[172:173], off offset:16
	global_load_dwordx2 v[188:189], v[174:175], off offset:-32
	global_load_dwordx2 v[190:191], v[174:175], off offset:-16
	global_load_dwordx2 v[192:193], v[174:175], off
	global_load_dwordx2 v[194:195], v[174:175], off offset:16
	ds_read_b128 v[0:3], v119 offset:8704
	ds_read_b128 v[4:7], v119
	ds_read_b128 v[126:129], v119 offset:32
	ds_read_b128 v[8:11], v124
	ds_read_b128 v[130:133], v124 offset:32
	s_waitcnt lgkmcnt(1)
	v_mfma_f32_32x32x16_bf16 v[16:31], v[8:11], v[4:7], 0
	ds_read_b128 v[134:137], v119 offset:8736
	v_mfma_f32_32x32x16_bf16 v[0:15], v[8:11], v[0:3], 0
	s_waitcnt lgkmcnt(1)
	v_mfma_f32_32x32x16_bf16 v[16:31], v[130:133], v[126:129], v[16:31]
	s_waitcnt lgkmcnt(0)
	v_mfma_f32_32x32x16_bf16 v[0:15], v[130:133], v[134:137], v[0:15]
	ds_read_b128 v[126:129], v119 offset:8768
	ds_read_b128 v[130:133], v119 offset:64
	ds_read_b128 v[134:137], v124 offset:64
	s_waitcnt lgkmcnt(0)
	v_mfma_f32_32x32x16_bf16 v[16:31], v[134:137], v[130:133], v[16:31]
	v_mfma_f32_32x32x16_bf16 v[0:15], v[134:137], v[126:129], v[0:15]
	ds_read_b128 v[126:129], v119 offset:8800
	ds_read_b128 v[130:133], v119 offset:96
	ds_read_b128 v[134:137], v124 offset:96
	s_waitcnt lgkmcnt(0)
	v_mfma_f32_32x32x16_bf16 v[16:31], v[134:137], v[130:133], v[16:31]
	v_mfma_f32_32x32x16_bf16 v[0:15], v[134:137], v[126:129], v[0:15]
	ds_read_b128 v[126:129], v124 offset:128
	ds_read_b128 v[130:133], v119 offset:128
	s_waitcnt lgkmcnt(0)
	v_mfma_f32_32x32x16_bf16 v[16:31], v[126:129], v[130:133], v[16:31]
	ds_read_b128 v[130:133], v119 offset:8832
	s_waitcnt lgkmcnt(0)
	v_mfma_f32_32x32x16_bf16 v[0:15], v[126:129], v[130:133], v[0:15]
	ds_read_b128 v[126:129], v124 offset:160
	ds_read_b128 v[130:133], v119 offset:160
	s_waitcnt lgkmcnt(0)
	v_mfma_f32_32x32x16_bf16 v[16:31], v[126:129], v[130:133], v[16:31]
	ds_read_b128 v[130:133], v119 offset:8864
	s_waitcnt lgkmcnt(0)
	v_mfma_f32_32x32x16_bf16 v[0:15], v[126:129], v[130:133], v[0:15]
	ds_read_b128 v[126:129], v124 offset:192
	ds_read_b128 v[130:133], v119 offset:192
	s_waitcnt lgkmcnt(0)
; DI unsigned pk2(float lo, float hi) { f32x2 v = {lo, hi}; bf16x2_t b = __builtin_convertvector(v, bf16x2_t); return __builtin_bit_cast(unsigned, b); }
; DI float bflo(unsigned u) { return __uint_as_float(u << 16); }
; DI float bfhi(unsigned u) { return __uint_as_float(u & 0xffff0000u); }
; __global__ void __launch_bounds__(NTHR) fwd_kernel(Args args) {
;     ...
;                             tgemm128<false>(acc, lds + 2 * TILE_B, lds + 3 * TILE_B, wid, lane);
;                             const int r32 = lane & 31, hi = lane >> 5;
; #pragma unroll
;                             for (int nt = 0; nt < 2; ++nt) {
;                                 const int p = 64 * (wid >> 2) + 32 * nt + r32; const float bias = args.in[I_SGUB][(l * 8 + g) * 128 + p];
;                                 const size_t off = (R0 + p) * RESTW + g * 128 + 32 * (wid & 3) + 4 * hi;
;                                 bf16_t* op = SGUO + (R0 + p) * 1024 + g * 128 + 32 * (wid & 3) + 4 * hi;
; #pragma unroll
;                                 for (int rg = 0; rg < 4; ++rg) {
;                                     const u32x2 su = *(const u32x2*)(REST + off + 8 * rg);
;                                     const float o0 = bflo(su.x) * (acc[nt][4 * rg] + bias), o1 = bfhi(su.x) * (acc[nt][4 * rg + 1] + bias), o2 = bflo(su.y) * (acc[nt][4 * rg + 2] + bias), o3 = bfhi(su.y) * (acc[nt][4 * rg + 3] + bias);
;                                     *(u32x2*)(op + 8 * rg) = (u32x2){pk2(o0, o1), pk2(o2, o3)};
;                                 }
;                             }
	v_mfma_f32_32x32x16_bf16 v[16:31], v[126:129], v[130:133], v[16:31]
	ds_read_b128 v[130:133], v119 offset:8896
	s_waitcnt lgkmcnt(0)
	v_mfma_f32_32x32x16_bf16 v[0:15], v[126:129], v[130:133], v[0:15]
	ds_read_b128 v[126:129], v124 offset:224
	ds_read_b128 v[130:133], v119 offset:224
	s_waitcnt lgkmcnt(0)
	v_mfma_f32_32x32x16_bf16 v[16:31], v[126:129], v[130:133], v[16:31]
	ds_read_b128 v[130:133], v119 offset:8928
	s_waitcnt lgkmcnt(0)
	v_mfma_f32_32x32x16_bf16 v[0:15], v[126:129], v[130:133], v[0:15]
	v_lshl_add_u64 v[150:151], v[104:105], 0, s[18:19]
	v_lshl_add_u64 v[152:153], v[106:107], 0, s[18:19]
	s_add_u32 s68, s68, 0x10000
	s_addc_u32 s69, s69, 0
	s_add_u32 s8, s8, 0x200
	s_addc_u32 s9, s9, 0
	v_add_u32_e32 v90, 0x80, v90
	v_lshl_add_u64 v[92:93], v[92:93], 0, s[44:45]
	v_lshl_add_u64 v[94:95], v[94:95], 0, s[44:45]
	v_lshl_add_u64 v[96:97], v[96:97], 0, s[44:45]
	v_lshl_add_u64 v[98:99], v[98:99], 0, s[44:45]
	v_lshl_add_u64 v[102:103], v[102:103], 0, s[44:45]
	v_lshl_add_u64 v[104:105], v[104:105], 0, s[44:45]
	v_lshl_add_u64 v[100:101], v[100:101], 0, s[44:45]
	v_lshl_add_u64 v[106:107], v[106:107], 0, s[44:45]
	s_cmp_eq_u32 s68, 0x20000
	s_waitcnt vmcnt(0)
	v_pk_add_f32 v[138:139], v[176:177], v[16:17] op_sel_hi:[0,1]
	v_pk_add_f32 v[140:141], v[176:177], v[18:19] op_sel_hi:[0,1]
	v_lshlrev_b32_e32 v142, 16, v178
	v_and_b32_e32 v143, 0xffff0000, v178
	v_lshlrev_b32_e32 v144, 16, v179
	v_and_b32_e32 v145, 0xffff0000, v179
	v_pk_mul_f32 v[138:139], v[138:139], v[142:143]
	v_pk_mul_f32 v[140:141], v[140:141], v[144:145]
	v_cvt_pk_bf16_f32 v138, v138, v139
	v_cvt_pk_bf16_f32 v139, v140, v141
	global_store_dwordx2 v[150:151], v[138:139], off offset:-32
	v_pk_add_f32 v[154:155], v[176:177], v[20:21] op_sel_hi:[0,1]
	v_pk_add_f32 v[156:157], v[176:177], v[22:23] op_sel_hi:[0,1]
	v_lshlrev_b32_e32 v158, 16, v180
	v_and_b32_e32 v159, 0xffff0000, v180
	v_lshlrev_b32_e32 v160, 16, v181
	v_and_b32_e32 v161, 0xffff0000, v181
	v_pk_mul_f32 v[154:155], v[154:155], v[158:159]
	v_pk_mul_f32 v[156:157], v[156:157], v[160:161]
	v_cvt_pk_bf16_f32 v154, v154, v155
	v_cvt_pk_bf16_f32 v155, v156, v157
	global_store_dwordx2 v[150:151], v[154:155], off offset:-16
	v_pk_add_f32 v[138:139], v[176:177], v[24:25] op_sel_hi:[0,1]
	v_pk_add_f32 v[140:141], v[176:177], v[26:27] op_sel_hi:[0,1]
	v_lshlrev_b32_e32 v142, 16, v182
	v_and_b32_e32 v143, 0xffff0000, v182
	v_lshlrev_b32_e32 v144, 16, v183
	v_and_b32_e32 v145, 0xffff0000, v183
	v_pk_mul_f32 v[138:139], v[138:139], v[142:143]
	v_pk_mul_f32 v[140:141], v[140:141], v[144:145]
	v_cvt_pk_bf16_f32 v138, v138, v139
	v_cvt_pk_bf16_f32 v139, v140, v141
	global_store_dwordx2 v[150:151], v[138:139], off
	v_pk_add_f32 v[154:155], v[176:177], v[28:29] op_sel_hi:[0,1]
	v_pk_add_f32 v[156:157], v[176:177], v[30:31] op_sel_hi:[0,1]
	v_lshlrev_b32_e32 v158, 16, v186
	v_and_b32_e32 v159, 0xffff0000, v186
	v_lshlrev_b32_e32 v160, 16, v187
	v_and_b32_e32 v161, 0xffff0000, v187
	v_pk_mul_f32 v[154:155], v[154:155], v[158:159]
	v_pk_mul_f32 v[156:157], v[156:157], v[160:161]
	v_cvt_pk_bf16_f32 v154, v154, v155
	v_cvt_pk_bf16_f32 v155, v156, v157
	global_store_dwordx2 v[150:151], v[154:155], off offset:16
	v_pk_add_f32 v[138:139], v[196:197], v[0:1] op_sel_hi:[0,1]
	v_pk_add_f32 v[140:141], v[196:197], v[2:3] op_sel_hi:[0,1]
	v_lshlrev_b32_e32 v142, 16, v188
	v_and_b32_e32 v143, 0xffff0000, v188
	v_lshlrev_b32_e32 v144, 16, v189
	v_and_b32_e32 v145, 0xffff0000, v189
	v_pk_mul_f32 v[138:139], v[138:139], v[142:143]
	v_pk_mul_f32 v[140:141], v[140:141], v[144:145]
	v_cvt_pk_bf16_f32 v138, v138, v139
	v_cvt_pk_bf16_f32 v139, v140, v141
	global_store_dwordx2 v[152:153], v[138:139], off offset:-32
	v_pk_add_f32 v[154:155], v[196:197], v[4:5] op_sel_hi:[0,1]
	v_pk_add_f32 v[156:157], v[196:197], v[6:7] op_sel_hi:[0,1]
	v_lshlrev_b32_e32 v158, 16, v190
	v_and_b32_e32 v159, 0xffff0000, v190
	v_lshlrev_b32_e32 v160, 16, v191
	v_and_b32_e32 v161, 0xffff0000, v191
	v_pk_mul_f32 v[154:155], v[154:155], v[158:159]
	v_pk_mul_f32 v[156:157], v[156:157], v[160:161]
	v_cvt_pk_bf16_f32 v154, v154, v155
	v_cvt_pk_bf16_f32 v155, v156, v157
	global_store_dwordx2 v[152:153], v[154:155], off offset:-16
	v_pk_add_f32 v[138:139], v[196:197], v[8:9] op_sel_hi:[0,1]
	v_pk_add_f32 v[140:141], v[196:197], v[10:11] op_sel_hi:[0,1]
	v_lshlrev_b32_e32 v142, 16, v192
	v_and_b32_e32 v143, 0xffff0000, v192
	v_lshlrev_b32_e32 v144, 16, v193
	v_and_b32_e32 v145, 0xffff0000, v193
	v_pk_mul_f32 v[138:139], v[138:139], v[142:143]
	v_pk_mul_f32 v[140:141], v[140:141], v[144:145]
	v_cvt_pk_bf16_f32 v138, v138, v139
	v_cvt_pk_bf16_f32 v139, v140, v141
	global_store_dwordx2 v[152:153], v[138:139], off
	v_pk_add_f32 v[154:155], v[196:197], v[12:13] op_sel_hi:[0,1]
	v_pk_add_f32 v[156:157], v[196:197], v[14:15] op_sel_hi:[0,1]
	v_lshlrev_b32_e32 v158, 16, v194
	v_and_b32_e32 v159, 0xffff0000, v194
	v_lshlrev_b32_e32 v160, 16, v195
	v_and_b32_e32 v161, 0xffff0000, v195
	v_pk_mul_f32 v[154:155], v[154:155], v[158:159]
	v_pk_mul_f32 v[156:157], v[156:157], v[160:161]
	v_cvt_pk_bf16_f32 v154, v154, v155
	v_cvt_pk_bf16_f32 v155, v156, v157
	global_store_dwordx2 v[152:153], v[154:155], off offset:16
	s_barrier
	s_cbranch_scc0 .LBB0_434
	s_add_i32 s11, s11, s34
	s_add_i32 s0, s0, s60
	s_cmp_ge_i32 s11, s10
	s_cbranch_scc0 .LBB0_429
